# table conversion in fp8 GEMM tails: second row of each iteration requested together with the first (own registers, copied into place), latency overlapped with the first row's conversion
# baseline (speedup 1.0000x reference)
.LBB0_576:
	s_add_i32 s13, s12, s39
	s_cmpk_lt_i32 s13, 0x4000
	s_cselect_b64 s[18:19], -1, 0
	s_add_i32 s20, s13, 0xffffc000
	s_cmpk_gt_i32 s13, 0x3fff
	s_cselect_b64 s[0:1], -1, 0
	s_and_b64 s[6:7], s[0:1], exec
	s_cselect_b32 s7, s94, s92
	s_cselect_b32 s20, s20, s13
	s_cselect_b32 s6, s95, s93
	s_add_u32 s22, s7, s14
	s_addc_u32 s23, s6, s15
	s_ashr_i32 s21, s20, 31
	s_lshl_b64 s[6:7], s[20:21], 13
	s_add_u32 s6, s22, s6
	s_addc_u32 s7, s23, s7
	v_lshl_add_u64 v[18:19], s[6:7], 0, v[34:35]
	global_load_dwordx4 v[2:5], v34, s[6:7]
	global_load_dwordx4 v[6:9], v34, s[6:7] offset:1024
	global_load_dwordx4 v[10:13], v34, s[6:7] offset:2048
	global_load_dwordx4 v[14:17], v34, s[6:7] offset:3072
	v_add_co_u32_e32 v30, vcc, s31, v18
	v_mov_b32_e32 v74, 1.0
	s_nop 0
	v_addc_co_u32_e32 v31, vcc, 0, v19, vcc
	global_load_dwordx4 v[18:21], v[30:31], off
	global_load_dwordx4 v[22:25], v[30:31], off offset:1024
	global_load_dwordx4 v[26:29], v[30:31], off offset:2048
	s_nop 0
	global_load_dwordx4 v[30:33], v[30:31], off offset:3072
	v_lshl_add_u64 v[146:147], s[6:7], 0, v[34:35]
	v_add_co_u32_e32 v146, vcc, 0x2000, v146
	s_nop 1
	v_addc_co_u32_e32 v147, vcc, 0, v147, vcc
	global_load_dwordx4 v[148:151], v[146:147], off
	global_load_dwordx4 v[152:155], v[146:147], off offset:1024
	global_load_dwordx4 v[156:159], v[146:147], off offset:2048
	global_load_dwordx4 v[160:163], v[146:147], off offset:3072
	v_add_co_u32_e32 v146, vcc, 0x1000, v146
	s_nop 1
	v_addc_co_u32_e32 v147, vcc, 0, v147, vcc
	global_load_dwordx4 v[164:167], v[146:147], off
	global_load_dwordx4 v[168:171], v[146:147], off offset:1024
	global_load_dwordx4 v[172:175], v[146:147], off offset:2048
	global_load_dwordx4 v[176:179], v[146:147], off offset:3072
	s_waitcnt vmcnt(8)
	v_max_f32_e64 v36, |v5|, |v5|
	v_max_f32_e64 v37, |v4|, |v4|
	v_max_f32_e64 v57, |v9|, |v9|
	v_max_f32_e64 v58, |v8|, |v8|
	v_max_f32_e64 v59, |v13|, |v13|
	v_max_f32_e64 v60, |v12|, |v12|
	v_max_f32_e64 v61, |v17|, |v17|
	v_max_f32_e64 v62, |v16|, |v16|
	v_max_f32_e32 v36, v37, v36
	v_max_f32_e32 v37, v58, v57
	v_max_f32_e32 v57, v60, v59
	v_max_f32_e32 v58, v62, v61
	v_max3_f32 v36, |v2|, |v3|, v36
	v_max3_f32 v37, |v6|, |v7|, v37
	v_max_f32_e64 v59, |v21|, |v21|
	v_max_f32_e64 v60, |v20|, |v20|
	v_max_f32_e64 v61, |v25|, |v25|
	v_max_f32_e64 v62, |v24|, |v24|
	v_max3_f32 v57, |v10|, |v11|, v57
	v_max3_f32 v58, |v14|, |v15|, v58
	v_max_f32_e64 v63, |v29|, |v29|
	v_max_f32_e64 v64, |v28|, |v28|
	v_max_f32_e64 v65, |v33|, |v33|
	v_max_f32_e64 v66, |v32|, |v32|
	v_max3_f32 v36, v36, 0, v37
	v_max_f32_e32 v37, v60, v59
	v_max_f32_e32 v59, v62, v61
	v_max_f32_e32 v60, v64, v63
	v_max_f32_e32 v61, v66, v65
	v_max3_f32 v36, v36, v57, v58
	v_max3_f32 v37, |v18|, |v19|, v37
	v_max3_f32 v57, |v22|, |v23|, v59
	v_max3_f32 v58, |v26|, |v27|, v60
	v_max3_f32 v59, |v30|, |v31|, v61
	v_max3_f32 v36, v36, v37, v57
	v_max3_f32 v36, v36, v58, v59
	ds_bpermute_b32 v37, v51, v36
	s_waitcnt lgkmcnt(0)
	v_max_f32_e32 v37, v37, v37
	v_max_f32_e32 v36, v36, v37
	ds_bpermute_b32 v37, v52, v36
	s_waitcnt lgkmcnt(0)
	v_max_f32_e32 v37, v37, v37
	v_max_f32_e32 v36, v36, v37
	ds_bpermute_b32 v37, v53, v36
	s_waitcnt lgkmcnt(0)
	v_max_f32_e32 v37, v37, v37
	v_max_f32_e32 v36, v36, v37
	ds_bpermute_b32 v37, v54, v36
	s_waitcnt lgkmcnt(0)
	v_max_f32_e32 v37, v37, v37
	v_max_f32_e32 v36, v36, v37
	ds_bpermute_b32 v37, v55, v36
	s_waitcnt lgkmcnt(0)
	v_max_f32_e32 v37, v37, v37
	v_max_f32_e32 v36, v36, v37
	ds_bpermute_b32 v37, v56, v36
	s_waitcnt lgkmcnt(0)
	v_max_f32_e32 v37, v37, v37
	v_max_f32_e32 v57, v36, v37
	v_cmp_lt_f32_e64 s[6:7], 0, v57
	s_and_saveexec_b64 s[22:23], s[6:7]
	s_cbranch_execz .LBB0_578
	v_cndmask_b32_e64 v36, v47, v48, s[0:1]
	v_div_scale_f32 v37, s[40:41], v57, v57, v36
	v_rcp_f32_e32 v58, v37
	v_div_scale_f32 v59, vcc, v36, v57, v36
	v_fma_f32 v60, -v37, v58, 1.0
	v_fmac_f32_e32 v58, v60, v58
	v_mul_f32_e32 v60, v59, v58
	v_fma_f32 v61, -v37, v60, v59
	v_fmac_f32_e32 v60, v61, v58
	v_fma_f32 v37, -v37, v60, v59
	v_div_fmas_f32 v37, v37, v58, v60
	v_div_fixup_f32 v74, v37, v57, v36

.LBB0_584:
	s_or_b64 exec, exec, s[18:19]
	s_add_i32 s20, s13, 1
	s_cmpk_lt_i32 s20, 0x4000
	s_cselect_b64 s[18:19], -1, 0
	s_addk_i32 s13, 0xc001
	s_cmpk_gt_i32 s20, 0x3fff
	s_cselect_b64 s[0:1], -1, 0
	s_and_b64 s[6:7], s[0:1], exec
	s_cselect_b32 s7, s94, s92
	s_cselect_b32 s20, s13, s20
	s_cselect_b32 s6, s95, s93
	s_add_u32 s13, s7, s14
	s_addc_u32 s22, s6, s15
	s_ashr_i32 s21, s20, 31
	s_lshl_b64 s[6:7], s[20:21], 13
	s_add_u32 s6, s13, s6
	s_addc_u32 s7, s22, s7
	v_lshl_add_u64 v[18:19], s[6:7], 0, v[34:35]
	v_add_co_u32_e32 v30, vcc, s31, v18
	v_mov_b32_e32 v74, 1.0
	s_nop 0
	v_addc_co_u32_e32 v31, vcc, 0, v19, vcc
	s_nop 0
	s_waitcnt vmcnt(8)
	v_mov_b32_e32 v2, v148
	v_mov_b32_e32 v3, v149
	v_mov_b32_e32 v4, v150
	v_mov_b32_e32 v5, v151
	v_mov_b32_e32 v6, v152
	v_mov_b32_e32 v7, v153
	v_mov_b32_e32 v8, v154
	v_mov_b32_e32 v9, v155
	v_mov_b32_e32 v10, v156
	v_mov_b32_e32 v11, v157
	v_mov_b32_e32 v12, v158
	v_mov_b32_e32 v13, v159
	v_mov_b32_e32 v14, v160
	v_mov_b32_e32 v15, v161
	v_mov_b32_e32 v16, v162
	v_mov_b32_e32 v17, v163
	v_mov_b32_e32 v18, v164
	v_mov_b32_e32 v19, v165
	v_mov_b32_e32 v20, v166
	v_mov_b32_e32 v21, v167
	v_mov_b32_e32 v22, v168
	v_mov_b32_e32 v23, v169
	v_mov_b32_e32 v24, v170
	v_mov_b32_e32 v25, v171
	v_mov_b32_e32 v26, v172
	v_mov_b32_e32 v27, v173
	v_mov_b32_e32 v28, v174
	v_mov_b32_e32 v29, v175
	v_mov_b32_e32 v30, v176
	v_mov_b32_e32 v31, v177
	v_mov_b32_e32 v32, v178
	v_mov_b32_e32 v33, v179
	v_max_f32_e64 v36, |v5|, |v5|
	v_max_f32_e64 v37, |v4|, |v4|
	v_max_f32_e64 v57, |v9|, |v9|
	v_max_f32_e64 v58, |v8|, |v8|
	v_max_f32_e64 v59, |v13|, |v13|
	v_max_f32_e64 v60, |v12|, |v12|
	v_max_f32_e64 v61, |v17|, |v17|
	v_max_f32_e64 v62, |v16|, |v16|
	v_max_f32_e32 v36, v37, v36
	v_max_f32_e32 v37, v58, v57
	v_max_f32_e32 v57, v60, v59
	v_max_f32_e32 v58, v62, v61
	v_max3_f32 v36, |v2|, |v3|, v36
	v_max3_f32 v37, |v6|, |v7|, v37
	v_max_f32_e64 v59, |v21|, |v21|
	v_max_f32_e64 v60, |v20|, |v20|
	v_max_f32_e64 v61, |v25|, |v25|
	v_max_f32_e64 v62, |v24|, |v24|
	v_max3_f32 v57, |v10|, |v11|, v57
	v_max3_f32 v58, |v14|, |v15|, v58
	v_max_f32_e64 v63, |v29|, |v29|
	v_max_f32_e64 v64, |v28|, |v28|
	v_max_f32_e64 v65, |v33|, |v33|
	v_max_f32_e64 v66, |v32|, |v32|
	v_max3_f32 v36, v36, 0, v37
	v_max_f32_e32 v37, v60, v59
	v_max_f32_e32 v59, v62, v61
	v_max_f32_e32 v60, v64, v63
	v_max_f32_e32 v61, v66, v65
	v_max3_f32 v36, v36, v57, v58
	v_max3_f32 v37, |v18|, |v19|, v37
	v_max3_f32 v57, |v22|, |v23|, v59
	v_max3_f32 v58, |v26|, |v27|, v60
	v_max3_f32 v59, |v30|, |v31|, v61
	v_max3_f32 v36, v36, v37, v57
	v_max3_f32 v36, v36, v58, v59
	ds_bpermute_b32 v37, v51, v36
	s_waitcnt lgkmcnt(0)
	v_max_f32_e32 v37, v37, v37
	v_max_f32_e32 v36, v36, v37
	ds_bpermute_b32 v37, v52, v36
	s_waitcnt lgkmcnt(0)
	v_max_f32_e32 v37, v37, v37
	v_max_f32_e32 v36, v36, v37
	ds_bpermute_b32 v37, v53, v36
	s_waitcnt lgkmcnt(0)
	v_max_f32_e32 v37, v37, v37
	v_max_f32_e32 v36, v36, v37
	ds_bpermute_b32 v37, v54, v36
	s_waitcnt lgkmcnt(0)
	v_max_f32_e32 v37, v37, v37
	v_max_f32_e32 v36, v36, v37
	ds_bpermute_b32 v37, v55, v36
	s_waitcnt lgkmcnt(0)
	v_max_f32_e32 v37, v37, v37
	v_max_f32_e32 v36, v36, v37
	ds_bpermute_b32 v37, v56, v36
	s_waitcnt lgkmcnt(0)
	v_max_f32_e32 v37, v37, v37
	v_max_f32_e32 v57, v36, v37
	v_cmp_lt_f32_e64 s[6:7], 0, v57
	s_and_saveexec_b64 s[22:23], s[6:7]
	s_cbranch_execz .LBB0_586
	v_cndmask_b32_e64 v36, v47, v48, s[0:1]
	v_div_scale_f32 v37, s[40:41], v57, v57, v36
	v_rcp_f32_e32 v58, v37
	v_div_scale_f32 v59, vcc, v36, v57, v36
	v_fma_f32 v60, -v37, v58, 1.0
	v_fmac_f32_e32 v58, v60, v58
	v_mul_f32_e32 v60, v59, v58
	v_fma_f32 v61, -v37, v60, v59
	v_fmac_f32_e32 v60, v61, v58
	v_fma_f32 v37, -v37, v60, v59
	v_div_fmas_f32 v37, v37, v58, v60
	v_div_fixup_f32 v74, v37, v57, v36

.LBB0_749:
	s_add_i32 s21, s20, s51
	s_cmpk_lt_i32 s21, 0x4000
	s_cselect_b64 s[26:27], -1, 0
	s_add_i32 s28, s21, 0xffffc000
	s_cmpk_gt_i32 s21, 0x3fff
	s_cselect_b64 s[0:1], -1, 0
	s_and_b64 s[10:11], s[0:1], exec
	s_cselect_b32 s11, s94, s92
	s_cselect_b32 s28, s28, s21
	s_cselect_b32 s10, s95, s93
	s_add_u32 s30, s11, s22
	s_addc_u32 s31, s10, s23
	s_ashr_i32 s29, s28, 31
	s_lshl_b64 s[10:11], s[28:29], 13
	s_add_u32 s10, s30, s10
	s_addc_u32 s11, s31, s11
	global_load_dwordx4 v[2:5], v34, s[10:11]
	v_lshl_add_u64 v[18:19], s[10:11], 0, v[34:35]
	v_add_co_u32_e32 v30, vcc, s40, v18
	v_mov_b32_e32 v74, 1.0
	s_nop 0
	v_addc_co_u32_e32 v31, vcc, 0, v19, vcc
	global_load_dwordx4 v[6:9], v34, s[10:11] offset:1024
	global_load_dwordx4 v[10:13], v34, s[10:11] offset:2048
	global_load_dwordx4 v[14:17], v34, s[10:11] offset:3072
	global_load_dwordx4 v[18:21], v[30:31], off
	global_load_dwordx4 v[22:25], v[30:31], off offset:1024
	global_load_dwordx4 v[26:29], v[30:31], off offset:2048
	s_nop 0
	global_load_dwordx4 v[30:33], v[30:31], off offset:3072
	v_lshl_add_u64 v[146:147], s[10:11], 0, v[34:35]
	v_add_co_u32_e32 v146, vcc, 0x2000, v146
	s_nop 1
	v_addc_co_u32_e32 v147, vcc, 0, v147, vcc
	global_load_dwordx4 v[148:151], v[146:147], off
	global_load_dwordx4 v[152:155], v[146:147], off offset:1024
	global_load_dwordx4 v[156:159], v[146:147], off offset:2048
	global_load_dwordx4 v[172:175], v[146:147], off offset:3072
	v_add_co_u32_e32 v146, vcc, 0x1000, v146
	s_nop 1
	v_addc_co_u32_e32 v147, vcc, 0, v147, vcc
	global_load_dwordx4 v[176:179], v[146:147], off
	global_load_dwordx4 v[180:183], v[146:147], off offset:1024
	global_load_dwordx4 v[192:195], v[146:147], off offset:2048
	global_load_dwordx4 v[196:199], v[146:147], off offset:3072
	s_waitcnt vmcnt(8)
	v_max3_f32 v36, |v2|, |v3|, |v4|
	v_max3_f32 v36, v36, |v5|, |v6|
	v_max3_f32 v36, v36, |v7|, |v8|
	v_max3_f32 v36, v36, |v9|, |v10|
	v_max3_f32 v36, v36, |v11|, |v12|
	v_max3_f32 v36, v36, |v13|, |v14|
	v_max3_f32 v36, v36, |v15|, |v16|
	v_max3_f32 v36, v36, |v17|, |v18|
	v_max3_f32 v36, v36, |v19|, |v20|
	v_max3_f32 v36, v36, |v21|, |v22|
	v_max3_f32 v36, v36, |v23|, |v24|
	v_max3_f32 v36, v36, |v25|, |v26|
	v_max3_f32 v36, v36, |v27|, |v28|
	v_max3_f32 v36, v36, |v29|, |v30|
	v_max3_f32 v36, v36, |v31|, |v32|
	v_max_f32_e64 v36, v36, |v33|
	ds_bpermute_b32 v37, v51, v36
	s_waitcnt lgkmcnt(0)
	v_max_f32_e32 v37, v37, v37
	v_max_f32_e32 v36, v36, v37
	ds_bpermute_b32 v37, v52, v36
	s_waitcnt lgkmcnt(0)
	v_max_f32_e32 v37, v37, v37
	v_max_f32_e32 v36, v36, v37
	ds_bpermute_b32 v37, v53, v36
	s_waitcnt lgkmcnt(0)
	v_max_f32_e32 v37, v37, v37
	v_max_f32_e32 v36, v36, v37
	ds_bpermute_b32 v37, v54, v36
	s_waitcnt lgkmcnt(0)
	v_max_f32_e32 v37, v37, v37
	v_max_f32_e32 v36, v36, v37
	ds_bpermute_b32 v37, v55, v36
	s_waitcnt lgkmcnt(0)
	v_max_f32_e32 v37, v37, v37
	v_max_f32_e32 v36, v36, v37
	ds_bpermute_b32 v37, v56, v36
	s_waitcnt lgkmcnt(0)
	v_max_f32_e32 v37, v37, v37
	v_max_f32_e32 v57, v36, v37
	v_cmp_lt_f32_e64 s[10:11], 0, v57
	s_and_saveexec_b64 s[30:31], s[10:11]
	s_cbranch_execz .LBB0_751
	v_cndmask_b32_e64 v36, v47, v48, s[0:1]
	v_div_scale_f32 v37, s[52:53], v57, v57, v36
	v_rcp_f32_e32 v58, v37
	v_div_scale_f32 v59, vcc, v36, v57, v36
	v_fma_f32 v60, -v37, v58, 1.0
	v_fmac_f32_e32 v58, v60, v58
	v_mul_f32_e32 v60, v59, v58
	v_fma_f32 v61, -v37, v60, v59
	v_fmac_f32_e32 v60, v61, v58
	v_fma_f32 v37, -v37, v60, v59
	v_div_fmas_f32 v37, v37, v58, v60
	v_div_fixup_f32 v74, v37, v57, v36

.LBB0_757:
	s_or_b64 exec, exec, s[26:27]
	s_add_i32 s28, s21, 1
	s_cmpk_lt_i32 s28, 0x4000
	s_cselect_b64 s[26:27], -1, 0
	s_addk_i32 s21, 0xc001
	s_cmpk_gt_i32 s28, 0x3fff
	s_cselect_b64 s[0:1], -1, 0
	s_and_b64 s[10:11], s[0:1], exec
	s_cselect_b32 s11, s94, s92
	s_cselect_b32 s28, s21, s28
	s_cselect_b32 s10, s95, s93
	s_add_u32 s21, s11, s22
	s_addc_u32 s30, s10, s23
	s_ashr_i32 s29, s28, 31
	s_lshl_b64 s[10:11], s[28:29], 13
	s_add_u32 s10, s21, s10
	s_addc_u32 s11, s30, s11
	v_lshl_add_u64 v[18:19], s[10:11], 0, v[34:35]
	v_add_co_u32_e32 v30, vcc, s40, v18
	v_mov_b32_e32 v74, 1.0
	s_nop 0
	v_addc_co_u32_e32 v31, vcc, 0, v19, vcc
	s_nop 0
	s_waitcnt vmcnt(8)
	v_mov_b32_e32 v2, v148
	v_mov_b32_e32 v3, v149
	v_mov_b32_e32 v4, v150
	v_mov_b32_e32 v5, v151
	v_mov_b32_e32 v6, v152
	v_mov_b32_e32 v7, v153
	v_mov_b32_e32 v8, v154
	v_mov_b32_e32 v9, v155
	v_mov_b32_e32 v10, v156
	v_mov_b32_e32 v11, v157
	v_mov_b32_e32 v12, v158
	v_mov_b32_e32 v13, v159
	v_mov_b32_e32 v14, v172
	v_mov_b32_e32 v15, v173
	v_mov_b32_e32 v16, v174
	v_mov_b32_e32 v17, v175
	v_mov_b32_e32 v18, v176
	v_mov_b32_e32 v19, v177
	v_mov_b32_e32 v20, v178
	v_mov_b32_e32 v21, v179
	v_mov_b32_e32 v22, v180
	v_mov_b32_e32 v23, v181
	v_mov_b32_e32 v24, v182
	v_mov_b32_e32 v25, v183
	v_mov_b32_e32 v26, v192
	v_mov_b32_e32 v27, v193
	v_mov_b32_e32 v28, v194
	v_mov_b32_e32 v29, v195
	v_mov_b32_e32 v30, v196
	v_mov_b32_e32 v31, v197
	v_mov_b32_e32 v32, v198
	v_mov_b32_e32 v33, v199
	v_max3_f32 v36, |v2|, |v3|, |v4|
	v_max3_f32 v36, v36, |v5|, |v6|
	v_max3_f32 v36, v36, |v7|, |v8|
	v_max3_f32 v36, v36, |v9|, |v10|
	v_max3_f32 v36, v36, |v11|, |v12|
	v_max3_f32 v36, v36, |v13|, |v14|
	v_max3_f32 v36, v36, |v15|, |v16|
	v_max3_f32 v36, v36, |v17|, |v18|
	v_max3_f32 v36, v36, |v19|, |v20|
	v_max3_f32 v36, v36, |v21|, |v22|
	v_max3_f32 v36, v36, |v23|, |v24|
	v_max3_f32 v36, v36, |v25|, |v26|
	v_max3_f32 v36, v36, |v27|, |v28|
	v_max3_f32 v36, v36, |v29|, |v30|
	v_max3_f32 v36, v36, |v31|, |v32|
	v_max_f32_e64 v36, v36, |v33|
	ds_bpermute_b32 v37, v51, v36
	s_waitcnt lgkmcnt(0)
	v_max_f32_e32 v37, v37, v37
	v_max_f32_e32 v36, v36, v37
	ds_bpermute_b32 v37, v52, v36
	s_waitcnt lgkmcnt(0)
	v_max_f32_e32 v37, v37, v37
	v_max_f32_e32 v36, v36, v37
	ds_bpermute_b32 v37, v53, v36
	s_waitcnt lgkmcnt(0)
	v_max_f32_e32 v37, v37, v37
	v_max_f32_e32 v36, v36, v37
	ds_bpermute_b32 v37, v54, v36
	s_waitcnt lgkmcnt(0)
	v_max_f32_e32 v37, v37, v37
	v_max_f32_e32 v36, v36, v37
	ds_bpermute_b32 v37, v55, v36
	s_waitcnt lgkmcnt(0)
	v_max_f32_e32 v37, v37, v37
	v_max_f32_e32 v36, v36, v37
	ds_bpermute_b32 v37, v56, v36
	s_waitcnt lgkmcnt(0)
	v_max_f32_e32 v37, v37, v37
	v_max_f32_e32 v57, v36, v37
	v_cmp_lt_f32_e64 s[10:11], 0, v57
	s_and_saveexec_b64 s[30:31], s[10:11]
	s_cbranch_execz .LBB0_759
	v_cndmask_b32_e64 v36, v47, v48, s[0:1]
	v_div_scale_f32 v37, s[52:53], v57, v57, v36
	v_rcp_f32_e32 v58, v37
	v_div_scale_f32 v59, vcc, v36, v57, v36
	v_fma_f32 v60, -v37, v58, 1.0
	v_fmac_f32_e32 v58, v60, v58
	v_mul_f32_e32 v60, v59, v58
	v_fma_f32 v61, -v37, v60, v59
	v_fmac_f32_e32 v60, v61, v58
	v_fma_f32 v37, -v37, v60, v59
	v_div_fmas_f32 v37, v37, v58, v60
	v_div_fixup_f32 v74, v37, v57, v36

.LBB0_911:
	s_add_i32 s21, s20, s51
	s_cmpk_lt_i32 s21, 0x4000
	s_cselect_b64 s[26:27], -1, 0
	s_add_i32 s28, s21, 0xffffc000
	s_cmpk_gt_i32 s21, 0x3fff
	s_cselect_b64 s[0:1], -1, 0
	s_and_b64 s[10:11], s[0:1], exec
	s_cselect_b32 s11, s94, s92
	s_cselect_b32 s28, s28, s21
	s_cselect_b32 s10, s95, s93
	s_add_u32 s30, s11, s22
	s_addc_u32 s31, s10, s23
	s_ashr_i32 s29, s28, 31
	s_lshl_b64 s[10:11], s[28:29], 13
	s_add_u32 s10, s30, s10
	s_addc_u32 s11, s31, s11
	global_load_dwordx4 v[2:5], v34, s[10:11]
	v_lshl_add_u64 v[18:19], s[10:11], 0, v[34:35]
	v_add_co_u32_e32 v30, vcc, s40, v18
	v_mov_b32_e32 v74, 1.0
	s_nop 0
	v_addc_co_u32_e32 v31, vcc, 0, v19, vcc
	global_load_dwordx4 v[6:9], v34, s[10:11] offset:1024
	global_load_dwordx4 v[10:13], v34, s[10:11] offset:2048
	global_load_dwordx4 v[14:17], v34, s[10:11] offset:3072
	global_load_dwordx4 v[18:21], v[30:31], off
	global_load_dwordx4 v[22:25], v[30:31], off offset:1024
	global_load_dwordx4 v[26:29], v[30:31], off offset:2048
	s_nop 0
	global_load_dwordx4 v[30:33], v[30:31], off offset:3072
	v_lshl_add_u64 v[146:147], s[10:11], 0, v[34:35]
	v_add_co_u32_e32 v146, vcc, 0x2000, v146
	s_nop 1
	v_addc_co_u32_e32 v147, vcc, 0, v147, vcc
	global_load_dwordx4 v[148:151], v[146:147], off
	global_load_dwordx4 v[152:155], v[146:147], off offset:1024
	global_load_dwordx4 v[156:159], v[146:147], off offset:2048
	global_load_dwordx4 v[160:163], v[146:147], off offset:3072
	v_add_co_u32_e32 v146, vcc, 0x1000, v146
	s_nop 1
	v_addc_co_u32_e32 v147, vcc, 0, v147, vcc
	global_load_dwordx4 v[164:167], v[146:147], off
	global_load_dwordx4 v[168:171], v[146:147], off offset:1024
	global_load_dwordx4 v[172:175], v[146:147], off offset:2048
	global_load_dwordx4 v[176:179], v[146:147], off offset:3072
	s_waitcnt vmcnt(8)
	v_max3_f32 v36, |v2|, |v3|, |v4|
	v_max3_f32 v36, v36, |v5|, |v6|
	v_max3_f32 v36, v36, |v7|, |v8|
	v_max3_f32 v36, v36, |v9|, |v10|
	v_max3_f32 v36, v36, |v11|, |v12|
	v_max3_f32 v36, v36, |v13|, |v14|
	v_max3_f32 v36, v36, |v15|, |v16|
	v_max3_f32 v36, v36, |v17|, |v18|
	v_max3_f32 v36, v36, |v19|, |v20|
	v_max3_f32 v36, v36, |v21|, |v22|
	v_max3_f32 v36, v36, |v23|, |v24|
	v_max3_f32 v36, v36, |v25|, |v26|
	v_max3_f32 v36, v36, |v27|, |v28|
	v_max3_f32 v36, v36, |v29|, |v30|
	v_max3_f32 v36, v36, |v31|, |v32|
	v_max_f32_e64 v36, v36, |v33|
	ds_bpermute_b32 v37, v51, v36
	s_waitcnt lgkmcnt(0)
	v_max_f32_e32 v37, v37, v37
	v_max_f32_e32 v36, v36, v37
	ds_bpermute_b32 v37, v52, v36
	s_waitcnt lgkmcnt(0)
	v_max_f32_e32 v37, v37, v37
	v_max_f32_e32 v36, v36, v37
	ds_bpermute_b32 v37, v53, v36
	s_waitcnt lgkmcnt(0)
	v_max_f32_e32 v37, v37, v37
	v_max_f32_e32 v36, v36, v37
	ds_bpermute_b32 v37, v54, v36
	s_waitcnt lgkmcnt(0)
	v_max_f32_e32 v37, v37, v37
	v_max_f32_e32 v36, v36, v37
	ds_bpermute_b32 v37, v55, v36
	s_waitcnt lgkmcnt(0)
	v_max_f32_e32 v37, v37, v37
	v_max_f32_e32 v36, v36, v37
	ds_bpermute_b32 v37, v56, v36
	s_waitcnt lgkmcnt(0)
	v_max_f32_e32 v37, v37, v37
	v_max_f32_e32 v57, v36, v37
	v_cmp_lt_f32_e64 s[10:11], 0, v57
	s_and_saveexec_b64 s[30:31], s[10:11]
	s_cbranch_execz .LBB0_913
	v_cndmask_b32_e64 v36, v47, v48, s[0:1]
	v_div_scale_f32 v37, s[52:53], v57, v57, v36
	v_rcp_f32_e32 v58, v37
	v_div_scale_f32 v59, vcc, v36, v57, v36
	v_fma_f32 v60, -v37, v58, 1.0
	v_fmac_f32_e32 v58, v60, v58
	v_mul_f32_e32 v60, v59, v58
	v_fma_f32 v61, -v37, v60, v59
	v_fmac_f32_e32 v60, v61, v58
	v_fma_f32 v37, -v37, v60, v59
	v_div_fmas_f32 v37, v37, v58, v60
	v_div_fixup_f32 v74, v37, v57, v36

.LBB0_919:
	s_or_b64 exec, exec, s[26:27]
	s_add_i32 s28, s21, 1
	s_cmpk_lt_i32 s28, 0x4000
	s_cselect_b64 s[26:27], -1, 0
	s_addk_i32 s21, 0xc001
	s_cmpk_gt_i32 s28, 0x3fff
	s_cselect_b64 s[0:1], -1, 0
	s_and_b64 s[10:11], s[0:1], exec
	s_cselect_b32 s11, s94, s92
	s_cselect_b32 s28, s21, s28
	s_cselect_b32 s10, s95, s93
	s_add_u32 s21, s11, s22
	s_addc_u32 s30, s10, s23
	s_ashr_i32 s29, s28, 31
	s_lshl_b64 s[10:11], s[28:29], 13
	s_add_u32 s10, s21, s10
	s_addc_u32 s11, s30, s11
	v_lshl_add_u64 v[18:19], s[10:11], 0, v[34:35]
	v_add_co_u32_e32 v30, vcc, s40, v18
	v_mov_b32_e32 v74, 1.0
	s_nop 0
	v_addc_co_u32_e32 v31, vcc, 0, v19, vcc
	s_nop 0
	s_waitcnt vmcnt(8)
	v_mov_b32_e32 v2, v148
	v_mov_b32_e32 v3, v149
	v_mov_b32_e32 v4, v150
	v_mov_b32_e32 v5, v151
	v_mov_b32_e32 v6, v152
	v_mov_b32_e32 v7, v153
	v_mov_b32_e32 v8, v154
	v_mov_b32_e32 v9, v155
	v_mov_b32_e32 v10, v156
	v_mov_b32_e32 v11, v157
	v_mov_b32_e32 v12, v158
	v_mov_b32_e32 v13, v159
	v_mov_b32_e32 v14, v160
	v_mov_b32_e32 v15, v161
	v_mov_b32_e32 v16, v162
	v_mov_b32_e32 v17, v163
	v_mov_b32_e32 v18, v164
	v_mov_b32_e32 v19, v165
	v_mov_b32_e32 v20, v166
	v_mov_b32_e32 v21, v167
	v_mov_b32_e32 v22, v168
	v_mov_b32_e32 v23, v169
	v_mov_b32_e32 v24, v170
	v_mov_b32_e32 v25, v171
	v_mov_b32_e32 v26, v172
	v_mov_b32_e32 v27, v173
	v_mov_b32_e32 v28, v174
	v_mov_b32_e32 v29, v175
	v_mov_b32_e32 v30, v176
	v_mov_b32_e32 v31, v177
	v_mov_b32_e32 v32, v178
	v_mov_b32_e32 v33, v179
	v_max3_f32 v36, |v2|, |v3|, |v4|
	v_max3_f32 v36, v36, |v5|, |v6|
	v_max3_f32 v36, v36, |v7|, |v8|
	v_max3_f32 v36, v36, |v9|, |v10|
	v_max3_f32 v36, v36, |v11|, |v12|
	v_max3_f32 v36, v36, |v13|, |v14|
	v_max3_f32 v36, v36, |v15|, |v16|
	v_max3_f32 v36, v36, |v17|, |v18|
	v_max3_f32 v36, v36, |v19|, |v20|
	v_max3_f32 v36, v36, |v21|, |v22|
	v_max3_f32 v36, v36, |v23|, |v24|
	v_max3_f32 v36, v36, |v25|, |v26|
	v_max3_f32 v36, v36, |v27|, |v28|
	v_max3_f32 v36, v36, |v29|, |v30|
	v_max3_f32 v36, v36, |v31|, |v32|
	v_max_f32_e64 v36, v36, |v33|
	ds_bpermute_b32 v37, v51, v36
	s_waitcnt lgkmcnt(0)
	v_max_f32_e32 v37, v37, v37
	v_max_f32_e32 v36, v36, v37
	ds_bpermute_b32 v37, v52, v36
	s_waitcnt lgkmcnt(0)
	v_max_f32_e32 v37, v37, v37
	v_max_f32_e32 v36, v36, v37
	ds_bpermute_b32 v37, v53, v36
	s_waitcnt lgkmcnt(0)
	v_max_f32_e32 v37, v37, v37
	v_max_f32_e32 v36, v36, v37
	ds_bpermute_b32 v37, v54, v36
	s_waitcnt lgkmcnt(0)
	v_max_f32_e32 v37, v37, v37
	v_max_f32_e32 v36, v36, v37
	ds_bpermute_b32 v37, v55, v36
	s_waitcnt lgkmcnt(0)
	v_max_f32_e32 v37, v37, v37
	v_max_f32_e32 v36, v36, v37
	ds_bpermute_b32 v37, v56, v36
	s_waitcnt lgkmcnt(0)
	v_max_f32_e32 v37, v37, v37
	v_max_f32_e32 v57, v36, v37
	v_cmp_lt_f32_e64 s[10:11], 0, v57
	s_and_saveexec_b64 s[30:31], s[10:11]
	s_cbranch_execz .LBB0_921
	v_cndmask_b32_e64 v36, v47, v48, s[0:1]
	v_div_scale_f32 v37, s[52:53], v57, v57, v36
	v_rcp_f32_e32 v58, v37
	v_div_scale_f32 v59, vcc, v36, v57, v36
	v_fma_f32 v60, -v37, v58, 1.0
	v_fmac_f32_e32 v58, v60, v58
	v_mul_f32_e32 v60, v59, v58
	v_fma_f32 v61, -v37, v60, v59
	v_fmac_f32_e32 v60, v61, v58
	v_fma_f32 v37, -v37, v60, v59
	v_div_fmas_f32 v37, v37, v58, v60
	v_div_fixup_f32 v74, v37, v57, v36

.LBB0_1944:
	s_add_i32 s19, s18, s47
	s_cmpk_lt_i32 s19, 0x4000
	s_cselect_b64 s[24:25], -1, 0
	s_add_i32 s26, s19, 0xffffc000
	s_cmpk_gt_i32 s19, 0x3fff
	s_cselect_b64 s[0:1], -1, 0
	s_and_b64 s[8:9], s[0:1], exec
	s_cselect_b32 s9, s94, s92
	s_cselect_b32 s26, s26, s19
	s_cselect_b32 s8, s95, s93
	s_add_u32 s28, s9, s20
	s_addc_u32 s29, s8, s21
	s_ashr_i32 s27, s26, 31
	s_lshl_b64 s[8:9], s[26:27], 13
	s_add_u32 s8, s28, s8
	s_addc_u32 s9, s29, s9
	v_lshl_add_u64 v[18:19], s[8:9], 0, v[34:35]
	global_load_dwordx4 v[2:5], v34, s[8:9]
	global_load_dwordx4 v[6:9], v34, s[8:9] offset:1024
	global_load_dwordx4 v[10:13], v34, s[8:9] offset:2048
	global_load_dwordx4 v[14:17], v34, s[8:9] offset:3072
	v_add_co_u32_e32 v30, vcc, s38, v18
	v_mov_b32_e32 v75, 1.0
	s_nop 0
	v_addc_co_u32_e32 v31, vcc, 0, v19, vcc
	global_load_dwordx4 v[18:21], v[30:31], off
	global_load_dwordx4 v[22:25], v[30:31], off offset:1024
	global_load_dwordx4 v[26:29], v[30:31], off offset:2048
	s_nop 0
	global_load_dwordx4 v[30:33], v[30:31], off offset:3072
	v_lshl_add_u64 v[146:147], s[8:9], 0, v[34:35]
	v_add_co_u32_e32 v146, vcc, 0x2000, v146
	s_nop 1
	v_addc_co_u32_e32 v147, vcc, 0, v147, vcc
	global_load_dwordx4 v[148:151], v[146:147], off
	global_load_dwordx4 v[152:155], v[146:147], off offset:1024
	global_load_dwordx4 v[156:159], v[146:147], off offset:2048
	global_load_dwordx4 v[160:163], v[146:147], off offset:3072
	v_add_co_u32_e32 v146, vcc, 0x1000, v146
	s_nop 1
	v_addc_co_u32_e32 v147, vcc, 0, v147, vcc
	global_load_dwordx4 v[164:167], v[146:147], off
	global_load_dwordx4 v[172:175], v[146:147], off offset:1024
	global_load_dwordx4 v[176:179], v[146:147], off offset:2048
	global_load_dwordx4 v[180:183], v[146:147], off offset:3072
	s_waitcnt vmcnt(8)
	v_max_f32_e64 v36, |v5|, |v5|
	v_max_f32_e64 v37, |v4|, |v4|
	v_max_f32_e64 v58, |v9|, |v9|
	v_max_f32_e64 v59, |v8|, |v8|
	v_max_f32_e64 v60, |v13|, |v13|
	v_max_f32_e64 v61, |v12|, |v12|
	v_max_f32_e64 v62, |v17|, |v17|
	v_max_f32_e64 v63, |v16|, |v16|
	v_max_f32_e32 v36, v37, v36
	v_max_f32_e32 v37, v59, v58
	v_max_f32_e32 v58, v61, v60
	v_max_f32_e32 v59, v63, v62
	v_max3_f32 v36, |v2|, |v3|, v36
	v_max3_f32 v37, |v6|, |v7|, v37
	v_max_f32_e64 v60, |v21|, |v21|
	v_max_f32_e64 v61, |v20|, |v20|
	v_max_f32_e64 v62, |v25|, |v25|
	v_max_f32_e64 v63, |v24|, |v24|
	v_max3_f32 v58, |v10|, |v11|, v58
	v_max3_f32 v59, |v14|, |v15|, v59
	v_max_f32_e64 v64, |v29|, |v29|
	v_max_f32_e64 v65, |v28|, |v28|
	v_max_f32_e64 v66, |v33|, |v33|
	v_max_f32_e64 v67, |v32|, |v32|
	v_max3_f32 v36, v36, 0, v37
	v_max_f32_e32 v37, v61, v60
	v_max_f32_e32 v60, v63, v62
	v_max_f32_e32 v61, v65, v64
	v_max_f32_e32 v62, v67, v66
	v_max3_f32 v36, v36, v58, v59
	v_max3_f32 v37, |v18|, |v19|, v37
	v_max3_f32 v58, |v22|, |v23|, v60
	v_max3_f32 v59, |v26|, |v27|, v61
	v_max3_f32 v60, |v30|, |v31|, v62
	v_max3_f32 v36, v36, v37, v58
	v_max3_f32 v36, v36, v59, v60
	ds_bpermute_b32 v37, v52, v36
	s_waitcnt lgkmcnt(0)
	v_max_f32_e32 v37, v37, v37
	v_max_f32_e32 v36, v36, v37
	ds_bpermute_b32 v37, v53, v36
	s_waitcnt lgkmcnt(0)
	v_max_f32_e32 v37, v37, v37
	v_max_f32_e32 v36, v36, v37
	ds_bpermute_b32 v37, v54, v36
	s_waitcnt lgkmcnt(0)
	v_max_f32_e32 v37, v37, v37
	v_max_f32_e32 v36, v36, v37
	ds_bpermute_b32 v37, v55, v36
	s_waitcnt lgkmcnt(0)
	v_max_f32_e32 v37, v37, v37
	v_max_f32_e32 v36, v36, v37
	ds_bpermute_b32 v37, v56, v36
	s_waitcnt lgkmcnt(0)
	v_max_f32_e32 v37, v37, v37
	v_max_f32_e32 v36, v36, v37
	ds_bpermute_b32 v37, v57, v36
	s_waitcnt lgkmcnt(0)
	v_max_f32_e32 v37, v37, v37
	v_max_f32_e32 v58, v36, v37
	v_cmp_lt_f32_e64 s[8:9], 0, v58
	s_and_saveexec_b64 s[28:29], s[8:9]
	s_cbranch_execz .LBB0_1946
	v_cndmask_b32_e64 v36, v48, v49, s[0:1]
	v_div_scale_f32 v37, s[54:55], v58, v58, v36
	v_rcp_f32_e32 v59, v37
	v_div_scale_f32 v60, vcc, v36, v58, v36
	v_fma_f32 v61, -v37, v59, 1.0
	v_fmac_f32_e32 v59, v61, v59
	v_mul_f32_e32 v61, v60, v59
	v_fma_f32 v62, -v37, v61, v60
	v_fmac_f32_e32 v61, v62, v59
	v_fma_f32 v37, -v37, v61, v60
	v_div_fmas_f32 v37, v37, v59, v61
	v_div_fixup_f32 v75, v37, v58, v36

.LBB0_1952:
	s_or_b64 exec, exec, s[24:25]
	s_add_i32 s26, s19, 1
	s_cmpk_lt_i32 s26, 0x4000
	s_cselect_b64 s[24:25], -1, 0
	s_addk_i32 s19, 0xc001
	s_cmpk_gt_i32 s26, 0x3fff
	s_cselect_b64 s[0:1], -1, 0
	s_and_b64 s[8:9], s[0:1], exec
	s_cselect_b32 s9, s94, s92
	s_cselect_b32 s26, s19, s26
	s_cselect_b32 s8, s95, s93
	s_add_u32 s19, s9, s20
	s_addc_u32 s28, s8, s21
	s_ashr_i32 s27, s26, 31
	s_lshl_b64 s[8:9], s[26:27], 13
	s_add_u32 s8, s19, s8
	s_addc_u32 s9, s28, s9
	v_lshl_add_u64 v[18:19], s[8:9], 0, v[34:35]
	v_add_co_u32_e32 v30, vcc, s38, v18
	v_mov_b32_e32 v75, 1.0
	s_nop 0
	v_addc_co_u32_e32 v31, vcc, 0, v19, vcc
	s_nop 0
	s_waitcnt vmcnt(8)
	v_mov_b32_e32 v2, v148
	v_mov_b32_e32 v3, v149
	v_mov_b32_e32 v4, v150
	v_mov_b32_e32 v5, v151
	v_mov_b32_e32 v6, v152
	v_mov_b32_e32 v7, v153
	v_mov_b32_e32 v8, v154
	v_mov_b32_e32 v9, v155
	v_mov_b32_e32 v10, v156
	v_mov_b32_e32 v11, v157
	v_mov_b32_e32 v12, v158
	v_mov_b32_e32 v13, v159
	v_mov_b32_e32 v14, v160
	v_mov_b32_e32 v15, v161
	v_mov_b32_e32 v16, v162
	v_mov_b32_e32 v17, v163
	v_mov_b32_e32 v18, v164
	v_mov_b32_e32 v19, v165
	v_mov_b32_e32 v20, v166
	v_mov_b32_e32 v21, v167
	v_mov_b32_e32 v22, v172
	v_mov_b32_e32 v23, v173
	v_mov_b32_e32 v24, v174
	v_mov_b32_e32 v25, v175
	v_mov_b32_e32 v26, v176
	v_mov_b32_e32 v27, v177
	v_mov_b32_e32 v28, v178
	v_mov_b32_e32 v29, v179
	v_mov_b32_e32 v30, v180
	v_mov_b32_e32 v31, v181
	v_mov_b32_e32 v32, v182
	v_mov_b32_e32 v33, v183
	v_max_f32_e64 v36, |v5|, |v5|
	v_max_f32_e64 v37, |v4|, |v4|
	v_max_f32_e64 v58, |v9|, |v9|
	v_max_f32_e64 v59, |v8|, |v8|
	v_max_f32_e64 v60, |v13|, |v13|
	v_max_f32_e64 v61, |v12|, |v12|
	v_max_f32_e64 v62, |v17|, |v17|
	v_max_f32_e64 v63, |v16|, |v16|
	v_max_f32_e32 v36, v37, v36
	v_max_f32_e32 v37, v59, v58
	v_max_f32_e32 v58, v61, v60
	v_max_f32_e32 v59, v63, v62
	v_max3_f32 v36, |v2|, |v3|, v36
	v_max3_f32 v37, |v6|, |v7|, v37
	v_max_f32_e64 v60, |v21|, |v21|
	v_max_f32_e64 v61, |v20|, |v20|
	v_max_f32_e64 v62, |v25|, |v25|
	v_max_f32_e64 v63, |v24|, |v24|
	v_max3_f32 v58, |v10|, |v11|, v58
	v_max3_f32 v59, |v14|, |v15|, v59
	v_max_f32_e64 v64, |v29|, |v29|
	v_max_f32_e64 v65, |v28|, |v28|
	v_max_f32_e64 v66, |v33|, |v33|
	v_max_f32_e64 v67, |v32|, |v32|
	v_max3_f32 v36, v36, 0, v37
	v_max_f32_e32 v37, v61, v60
	v_max_f32_e32 v60, v63, v62
	v_max_f32_e32 v61, v65, v64
	v_max_f32_e32 v62, v67, v66
	v_max3_f32 v36, v36, v58, v59
	v_max3_f32 v37, |v18|, |v19|, v37
	v_max3_f32 v58, |v22|, |v23|, v60
	v_max3_f32 v59, |v26|, |v27|, v61
	v_max3_f32 v60, |v30|, |v31|, v62
	v_max3_f32 v36, v36, v37, v58
	v_max3_f32 v36, v36, v59, v60
	ds_bpermute_b32 v37, v52, v36
	s_waitcnt lgkmcnt(0)
	v_max_f32_e32 v37, v37, v37
	v_max_f32_e32 v36, v36, v37
	ds_bpermute_b32 v37, v53, v36
	s_waitcnt lgkmcnt(0)
	v_max_f32_e32 v37, v37, v37
	v_max_f32_e32 v36, v36, v37
	ds_bpermute_b32 v37, v54, v36
	s_waitcnt lgkmcnt(0)
	v_max_f32_e32 v37, v37, v37
	v_max_f32_e32 v36, v36, v37
	ds_bpermute_b32 v37, v55, v36
	s_waitcnt lgkmcnt(0)
	v_max_f32_e32 v37, v37, v37
	v_max_f32_e32 v36, v36, v37
	ds_bpermute_b32 v37, v56, v36
	s_waitcnt lgkmcnt(0)
	v_max_f32_e32 v37, v37, v37
	v_max_f32_e32 v36, v36, v37
	ds_bpermute_b32 v37, v57, v36
	s_waitcnt lgkmcnt(0)
	v_max_f32_e32 v37, v37, v37
	v_max_f32_e32 v58, v36, v37
	v_cmp_lt_f32_e64 s[8:9], 0, v58
	s_and_saveexec_b64 s[28:29], s[8:9]
	s_cbranch_execz .LBB0_1954
	v_cndmask_b32_e64 v36, v48, v49, s[0:1]
	v_div_scale_f32 v37, s[54:55], v58, v58, v36
	v_rcp_f32_e32 v59, v37
	v_div_scale_f32 v60, vcc, v36, v58, v36
	v_fma_f32 v61, -v37, v59, 1.0
	v_fmac_f32_e32 v59, v61, v59
	v_mul_f32_e32 v61, v60, v59
	v_fma_f32 v62, -v37, v61, v60
	v_fmac_f32_e32 v61, v62, v59
	v_fma_f32 v37, -v37, v61, v60
	v_div_fmas_f32 v37, v37, v59, v61
	v_div_fixup_f32 v75, v37, v58, v36

.LBB0_2479:
	s_add_i32 s15, s14, s41
	s_cmpk_lt_i32 s15, 0x4000
	s_cselect_b64 s[20:21], -1, 0
	s_add_i32 s22, s15, 0xffffc000
	s_cmpk_gt_i32 s15, 0x3fff
	s_cselect_b64 s[0:1], -1, 0
	s_and_b64 s[6:7], s[0:1], exec
	s_cselect_b32 s7, s94, s92
	s_cselect_b32 s22, s22, s15
	s_cselect_b32 s6, s95, s93
	s_add_u32 s24, s7, s16
	s_addc_u32 s25, s6, s17
	s_ashr_i32 s23, s22, 31
	s_lshl_b64 s[6:7], s[22:23], 13
	s_add_u32 s6, s24, s6
	s_addc_u32 s7, s25, s7
	v_lshl_add_u64 v[18:19], s[6:7], 0, v[34:35]
	global_load_dwordx4 v[2:5], v34, s[6:7]
	global_load_dwordx4 v[6:9], v34, s[6:7] offset:1024
	global_load_dwordx4 v[10:13], v34, s[6:7] offset:2048
	global_load_dwordx4 v[14:17], v34, s[6:7] offset:3072
	v_add_co_u32_e32 v30, vcc, s34, v18
	v_mov_b32_e32 v75, 1.0
	s_nop 0
	v_addc_co_u32_e32 v31, vcc, 0, v19, vcc
	global_load_dwordx4 v[18:21], v[30:31], off
	global_load_dwordx4 v[22:25], v[30:31], off offset:1024
	global_load_dwordx4 v[26:29], v[30:31], off offset:2048
	s_nop 0
	global_load_dwordx4 v[30:33], v[30:31], off offset:3072
	v_lshl_add_u64 v[146:147], s[6:7], 0, v[34:35]
	v_add_co_u32_e32 v146, vcc, 0x2000, v146
	s_nop 1
	v_addc_co_u32_e32 v147, vcc, 0, v147, vcc
	global_load_dwordx4 v[148:151], v[146:147], off
	global_load_dwordx4 v[152:155], v[146:147], off offset:1024
	global_load_dwordx4 v[156:159], v[146:147], off offset:2048
	global_load_dwordx4 v[160:163], v[146:147], off offset:3072
	v_add_co_u32_e32 v146, vcc, 0x1000, v146
	s_nop 1
	v_addc_co_u32_e32 v147, vcc, 0, v147, vcc
	global_load_dwordx4 v[164:167], v[146:147], off
	global_load_dwordx4 v[172:175], v[146:147], off offset:1024
	global_load_dwordx4 v[176:179], v[146:147], off offset:2048
	global_load_dwordx4 v[180:183], v[146:147], off offset:3072
	s_waitcnt vmcnt(8)
	v_max_f32_e64 v36, |v5|, |v5|
	v_max_f32_e64 v37, |v4|, |v4|
	v_max_f32_e64 v58, |v9|, |v9|
	v_max_f32_e64 v59, |v8|, |v8|
	v_max_f32_e64 v60, |v13|, |v13|
	v_max_f32_e64 v61, |v12|, |v12|
	v_max_f32_e64 v62, |v17|, |v17|
	v_max_f32_e64 v63, |v16|, |v16|
	v_max_f32_e32 v36, v37, v36
	v_max_f32_e32 v37, v59, v58
	v_max_f32_e32 v58, v61, v60
	v_max_f32_e32 v59, v63, v62
	v_max3_f32 v36, |v2|, |v3|, v36
	v_max3_f32 v37, |v6|, |v7|, v37
	v_max_f32_e64 v60, |v21|, |v21|
	v_max_f32_e64 v61, |v20|, |v20|
	v_max_f32_e64 v62, |v25|, |v25|
	v_max_f32_e64 v63, |v24|, |v24|
	v_max3_f32 v58, |v10|, |v11|, v58
	v_max3_f32 v59, |v14|, |v15|, v59
	v_max_f32_e64 v64, |v29|, |v29|
	v_max_f32_e64 v65, |v28|, |v28|
	v_max_f32_e64 v66, |v33|, |v33|
	v_max_f32_e64 v67, |v32|, |v32|
	v_max3_f32 v36, v36, 0, v37
	v_max_f32_e32 v37, v61, v60
	v_max_f32_e32 v60, v63, v62
	v_max_f32_e32 v61, v65, v64
	v_max_f32_e32 v62, v67, v66
	v_max3_f32 v36, v36, v58, v59
	v_max3_f32 v37, |v18|, |v19|, v37
	v_max3_f32 v58, |v22|, |v23|, v60
	v_max3_f32 v59, |v26|, |v27|, v61
	v_max3_f32 v60, |v30|, |v31|, v62
	v_max3_f32 v36, v36, v37, v58
	v_max3_f32 v36, v36, v59, v60
	ds_bpermute_b32 v37, v52, v36
	s_waitcnt lgkmcnt(0)
	v_max_f32_e32 v37, v37, v37
	v_max_f32_e32 v36, v36, v37
	ds_bpermute_b32 v37, v53, v36
	s_waitcnt lgkmcnt(0)
	v_max_f32_e32 v37, v37, v37
	v_max_f32_e32 v36, v36, v37
	ds_bpermute_b32 v37, v54, v36
	s_waitcnt lgkmcnt(0)
	v_max_f32_e32 v37, v37, v37
	v_max_f32_e32 v36, v36, v37
	ds_bpermute_b32 v37, v55, v36
	s_waitcnt lgkmcnt(0)
	v_max_f32_e32 v37, v37, v37
	v_max_f32_e32 v36, v36, v37
	ds_bpermute_b32 v37, v56, v36
	s_waitcnt lgkmcnt(0)
	v_max_f32_e32 v37, v37, v37
	v_max_f32_e32 v36, v36, v37
	ds_bpermute_b32 v37, v57, v36
	s_waitcnt lgkmcnt(0)
	v_max_f32_e32 v37, v37, v37
	v_max_f32_e32 v58, v36, v37
	v_cmp_lt_f32_e64 s[6:7], 0, v58
	s_and_saveexec_b64 s[24:25], s[6:7]
	s_cbranch_execz .LBB0_2481
	v_cndmask_b32_e64 v36, v48, v49, s[0:1]
	v_div_scale_f32 v37, s[42:43], v58, v58, v36
	v_rcp_f32_e32 v59, v37
	v_div_scale_f32 v60, vcc, v36, v58, v36
	v_fma_f32 v61, -v37, v59, 1.0
	v_fmac_f32_e32 v59, v61, v59
	v_mul_f32_e32 v61, v60, v59
	v_fma_f32 v62, -v37, v61, v60
	v_fmac_f32_e32 v61, v62, v59
	v_fma_f32 v37, -v37, v61, v60
	v_div_fmas_f32 v37, v37, v59, v61
	v_div_fixup_f32 v75, v37, v58, v36

.LBB0_2487:
	s_or_b64 exec, exec, s[20:21]
	s_add_i32 s22, s15, 1
	s_cmpk_lt_i32 s22, 0x4000
	s_cselect_b64 s[20:21], -1, 0
	s_addk_i32 s15, 0xc001
	s_cmpk_gt_i32 s22, 0x3fff
	s_cselect_b64 s[0:1], -1, 0
	s_and_b64 s[6:7], s[0:1], exec
	s_cselect_b32 s7, s94, s92
	s_cselect_b32 s22, s15, s22
	s_cselect_b32 s6, s95, s93
	s_add_u32 s15, s7, s16
	s_addc_u32 s24, s6, s17
	s_ashr_i32 s23, s22, 31
	s_lshl_b64 s[6:7], s[22:23], 13
	s_add_u32 s6, s15, s6
	s_addc_u32 s7, s24, s7
	v_lshl_add_u64 v[18:19], s[6:7], 0, v[34:35]
	v_add_co_u32_e32 v30, vcc, s34, v18
	v_mov_b32_e32 v75, 1.0
	s_nop 0
	v_addc_co_u32_e32 v31, vcc, 0, v19, vcc
	s_nop 0
	s_waitcnt vmcnt(8)
	v_mov_b32_e32 v2, v148
	v_mov_b32_e32 v3, v149
	v_mov_b32_e32 v4, v150
	v_mov_b32_e32 v5, v151
	v_mov_b32_e32 v6, v152
	v_mov_b32_e32 v7, v153
	v_mov_b32_e32 v8, v154
	v_mov_b32_e32 v9, v155
	v_mov_b32_e32 v10, v156
	v_mov_b32_e32 v11, v157
	v_mov_b32_e32 v12, v158
	v_mov_b32_e32 v13, v159
	v_mov_b32_e32 v14, v160
	v_mov_b32_e32 v15, v161
	v_mov_b32_e32 v16, v162
	v_mov_b32_e32 v17, v163
	v_mov_b32_e32 v18, v164
	v_mov_b32_e32 v19, v165
	v_mov_b32_e32 v20, v166
	v_mov_b32_e32 v21, v167
	v_mov_b32_e32 v22, v172
	v_mov_b32_e32 v23, v173
	v_mov_b32_e32 v24, v174
	v_mov_b32_e32 v25, v175
	v_mov_b32_e32 v26, v176
	v_mov_b32_e32 v27, v177
	v_mov_b32_e32 v28, v178
	v_mov_b32_e32 v29, v179
	v_mov_b32_e32 v30, v180
	v_mov_b32_e32 v31, v181
	v_mov_b32_e32 v32, v182
	v_mov_b32_e32 v33, v183
	v_max_f32_e64 v36, |v5|, |v5|
	v_max_f32_e64 v37, |v4|, |v4|
	v_max_f32_e64 v58, |v9|, |v9|
	v_max_f32_e64 v59, |v8|, |v8|
	v_max_f32_e64 v60, |v13|, |v13|
	v_max_f32_e64 v61, |v12|, |v12|
	v_max_f32_e64 v62, |v17|, |v17|
	v_max_f32_e64 v63, |v16|, |v16|
	v_max_f32_e32 v36, v37, v36
	v_max_f32_e32 v37, v59, v58
	v_max_f32_e32 v58, v61, v60
	v_max_f32_e32 v59, v63, v62
	v_max3_f32 v36, |v2|, |v3|, v36
	v_max3_f32 v37, |v6|, |v7|, v37
	v_max_f32_e64 v60, |v21|, |v21|
	v_max_f32_e64 v61, |v20|, |v20|
	v_max_f32_e64 v62, |v25|, |v25|
	v_max_f32_e64 v63, |v24|, |v24|
	v_max3_f32 v58, |v10|, |v11|, v58
	v_max3_f32 v59, |v14|, |v15|, v59
	v_max_f32_e64 v64, |v29|, |v29|
	v_max_f32_e64 v65, |v28|, |v28|
	v_max_f32_e64 v66, |v33|, |v33|
	v_max_f32_e64 v67, |v32|, |v32|
	v_max3_f32 v36, v36, 0, v37
	v_max_f32_e32 v37, v61, v60
	v_max_f32_e32 v60, v63, v62
	v_max_f32_e32 v61, v65, v64
	v_max_f32_e32 v62, v67, v66
	v_max3_f32 v36, v36, v58, v59
	v_max3_f32 v37, |v18|, |v19|, v37
	v_max3_f32 v58, |v22|, |v23|, v60
	v_max3_f32 v59, |v26|, |v27|, v61
	v_max3_f32 v60, |v30|, |v31|, v62
	v_max3_f32 v36, v36, v37, v58
	v_max3_f32 v36, v36, v59, v60
	ds_bpermute_b32 v37, v52, v36
	s_waitcnt lgkmcnt(0)
	v_max_f32_e32 v37, v37, v37
	v_max_f32_e32 v36, v36, v37
	ds_bpermute_b32 v37, v53, v36
	s_waitcnt lgkmcnt(0)
	v_max_f32_e32 v37, v37, v37
	v_max_f32_e32 v36, v36, v37
	ds_bpermute_b32 v37, v54, v36
	s_waitcnt lgkmcnt(0)
	v_max_f32_e32 v37, v37, v37
	v_max_f32_e32 v36, v36, v37
	ds_bpermute_b32 v37, v55, v36
	s_waitcnt lgkmcnt(0)
	v_max_f32_e32 v37, v37, v37
	v_max_f32_e32 v36, v36, v37
	ds_bpermute_b32 v37, v56, v36
	s_waitcnt lgkmcnt(0)
	v_max_f32_e32 v37, v37, v37
	v_max_f32_e32 v36, v36, v37
	ds_bpermute_b32 v37, v57, v36
	s_waitcnt lgkmcnt(0)
	v_max_f32_e32 v37, v37, v37
	v_max_f32_e32 v58, v36, v37
	v_cmp_lt_f32_e64 s[6:7], 0, v58
	s_and_saveexec_b64 s[24:25], s[6:7]
	s_cbranch_execz .LBB0_2489
	v_cndmask_b32_e64 v36, v48, v49, s[0:1]
	v_div_scale_f32 v37, s[42:43], v58, v58, v36
	v_rcp_f32_e32 v59, v37
	v_div_scale_f32 v60, vcc, v36, v58, v36
	v_fma_f32 v61, -v37, v59, 1.0
	v_fmac_f32_e32 v59, v61, v59
	v_mul_f32_e32 v61, v60, v59
	v_fma_f32 v62, -v37, v61, v60
	v_fmac_f32_e32 v61, v62, v59
	v_fma_f32 v37, -v37, v61, v60
	v_div_fmas_f32 v37, v37, v59, v61
	v_div_fixup_f32 v75, v37, v58, v36
